# rmsnorm gate projections (layers 1-3): the 8-way transpose-reduce done with v_permlane32/16_swap and DPP row ops instead of ten serialized ds_bpermute round trips per row; layer-0 instance: last three
# baseline (speedup 1.0000x reference)
; template <bool BIN, bool WRITE_U> __device__ __forceinline__ void norm_phase(const void* hin_, const float* gain, bf16* U, const float* Wg, int ldw, int goff, int ng, float* GATE, float* RSTD, unsigned char* lds) {
;     ...
;         if (ng > 0) {
;             float acc[8];
; #pragma unroll
;             for (int g = 0; g < 8; ++g) acc[g] = 0.f;
; #pragma unroll
;             for (int j = 0; j < 4; ++j)
; #pragma unroll
;                 for (int e = 0; e < 4; ++e) { const int k = 4 * (lane + 64 * j) + e; const f32x4 w0 = *(const f32x4*)(wl + k * 8), w1 = *(const f32x4*)(wl + k * 8 + 4); const float x = v[j][e];
;                     acc[0] += x * w0.x; acc[1] += x * w0.y; acc[2] += x * w0.z; acc[3] += x * w0.w; acc[4] += x * w1.x; acc[5] += x * w1.y; acc[6] += x * w1.z; acc[7] += x * w1.w; }
;             const bool h5 = (lane & 32) != 0, h4 = (lane & 16) != 0, h3 = (lane & 8) != 0;
;             float b4[4], c2[2];
; #pragma unroll
;             for (int i = 0; i < 4; ++i) { const float snd = h5 ? acc[i] : acc[i + 4], kp = h5 ? acc[i + 4] : acc[i]; b4[i] = kp + __shfl_xor(snd, 32); }
; #pragma unroll
;             for (int i = 0; i < 2; ++i) { const float snd = h4 ? b4[i] : b4[i + 2], kp = h4 ? b4[i + 2] : b4[i]; c2[i] = kp + __shfl_xor(snd, 16); }
;             float dsum; { const float snd = h3 ? c2[0] : c2[1], kp = h3 ? c2[1] : c2[0]; dsum = kp + __shfl_xor(snd, 8); }
;             dsum += __shfl_xor(dsum, 4); dsum += __shfl_xor(dsum, 2); dsum += __shfl_xor(dsum, 1);
;             if ((lane & 7) == 0) GATE[(size_t)row * 8 + ((lane >> 3) & 1) + 2 * ((lane >> 4) & 1) + 4 * ((lane >> 5) & 1)] = dsum * rstd;
.LBB0_198:
	s_or_b64 exec, exec, s[12:13]
	v_fma_f32 v180, v158, v26, 0
	v_fma_f32 v187, v158, v30, 0
	v_fmac_f32_e32 v180, v159, v34
	v_fmac_f32_e32 v187, v159, v38
	v_fmac_f32_e32 v180, v160, v42
	v_fmac_f32_e32 v187, v160, v46
	v_fmac_f32_e32 v180, v161, v54
	v_fmac_f32_e32 v187, v161, v58
	v_fma_f32 v181, v158, v27, 0
	v_fma_f32 v182, v158, v28, 0
	v_fma_f32 v183, v158, v29, 0
	v_fma_f32 v198, v158, v31, 0
	v_fma_f32 v199, v158, v32, 0
	v_fma_f32 v158, v158, v33, 0
	v_fmac_f32_e32 v180, v50, v62
	v_fmac_f32_e32 v187, v50, v66
	v_fmac_f32_e32 v181, v159, v35
	v_fmac_f32_e32 v182, v159, v36
	v_fmac_f32_e32 v183, v159, v37
	v_fmac_f32_e32 v198, v159, v39
	v_fmac_f32_e32 v199, v159, v40
	v_fmac_f32_e32 v158, v159, v41
	v_fmac_f32_e32 v180, v51, v70
	v_fmac_f32_e32 v187, v51, v74
	v_fmac_f32_e32 v181, v160, v43
	v_fmac_f32_e32 v182, v160, v44
	v_fmac_f32_e32 v183, v160, v45
	v_fmac_f32_e32 v198, v160, v47
	v_fmac_f32_e32 v199, v160, v48
	v_fmac_f32_e32 v158, v160, v49
	v_fmac_f32_e32 v180, v52, v78
	v_fmac_f32_e32 v187, v52, v82
	v_fmac_f32_e32 v181, v161, v55
	v_fmac_f32_e32 v182, v161, v56
	v_fmac_f32_e32 v183, v161, v57
	v_fmac_f32_e32 v198, v161, v59
	v_fmac_f32_e32 v199, v161, v60
	v_fmac_f32_e32 v158, v161, v61
	v_fmac_f32_e32 v180, v53, v86
	v_fmac_f32_e32 v187, v53, v90
	v_fmac_f32_e32 v181, v50, v63
	v_fmac_f32_e32 v182, v50, v64
	v_fmac_f32_e32 v183, v50, v65
	v_fmac_f32_e32 v198, v50, v67
	v_fmac_f32_e32 v199, v50, v68
	v_fmac_f32_e32 v158, v50, v69
	v_fmac_f32_e32 v180, v22, v94
	v_fmac_f32_e32 v187, v22, v98
	v_fmac_f32_e32 v181, v51, v71
	v_fmac_f32_e32 v182, v51, v72
	v_fmac_f32_e32 v183, v51, v73
	v_fmac_f32_e32 v198, v51, v75
	v_fmac_f32_e32 v199, v51, v76
	v_fmac_f32_e32 v158, v51, v77
	v_fmac_f32_e32 v180, v23, v102
	v_fmac_f32_e32 v187, v23, v106
	v_fmac_f32_e32 v181, v52, v79
	v_fmac_f32_e32 v182, v52, v80
	v_fmac_f32_e32 v183, v52, v81
	v_fmac_f32_e32 v198, v52, v83
	v_fmac_f32_e32 v199, v52, v84
	v_fmac_f32_e32 v158, v52, v85
	v_fmac_f32_e32 v180, v24, v110
	v_fmac_f32_e32 v187, v24, v114
	v_fmac_f32_e32 v181, v53, v87
	v_fmac_f32_e32 v182, v53, v88
	v_fmac_f32_e32 v183, v53, v89
	v_fmac_f32_e32 v198, v53, v91
	v_fmac_f32_e32 v199, v53, v92
	v_fmac_f32_e32 v158, v53, v93
	v_fmac_f32_e32 v180, v25, v118
	v_fmac_f32_e32 v187, v25, v122
	v_fmac_f32_e32 v181, v22, v95
	v_fmac_f32_e32 v182, v22, v96
	v_fmac_f32_e32 v183, v22, v97
	v_fmac_f32_e32 v198, v22, v99
	v_fmac_f32_e32 v199, v22, v100
	v_fmac_f32_e32 v158, v22, v101
	v_fmac_f32_e32 v180, v2, v126
	v_fmac_f32_e32 v187, v2, v130
	v_fmac_f32_e32 v181, v23, v103
	v_fmac_f32_e32 v182, v23, v104
	v_fmac_f32_e32 v183, v23, v105
	v_fmac_f32_e32 v198, v23, v107
	v_fmac_f32_e32 v199, v23, v108
	v_fmac_f32_e32 v158, v23, v109
	v_fmac_f32_e32 v180, v3, v134
	v_fmac_f32_e32 v187, v3, v138
	v_fmac_f32_e32 v181, v24, v111
	v_fmac_f32_e32 v182, v24, v112
	v_fmac_f32_e32 v183, v24, v113
	v_fmac_f32_e32 v198, v24, v115
	v_fmac_f32_e32 v199, v24, v116
	v_fmac_f32_e32 v158, v24, v117
	v_fmac_f32_e32 v180, v4, v142
	v_fmac_f32_e32 v187, v4, v146
	v_fmac_f32_e32 v181, v25, v119
	v_fmac_f32_e32 v182, v25, v120
	v_fmac_f32_e32 v183, v25, v121
	v_fmac_f32_e32 v198, v25, v123
	v_fmac_f32_e32 v199, v25, v124
	v_fmac_f32_e32 v158, v25, v125
	v_fmac_f32_e32 v180, v5, v150
	v_fmac_f32_e32 v187, v5, v154
	v_fmac_f32_e32 v181, v2, v127
	v_fmac_f32_e32 v182, v2, v128
	v_fmac_f32_e32 v183, v2, v129
	v_fmac_f32_e32 v198, v2, v131
	v_fmac_f32_e32 v199, v2, v132
	v_fmac_f32_e32 v158, v2, v133
	v_cndmask_b32_e64 v2, v180, v187, s[4:5]
	ds_bpermute_b32 v2, v197, v2
	v_fmac_f32_e32 v181, v3, v135
	v_fmac_f32_e32 v198, v3, v139
	v_fmac_f32_e32 v182, v3, v136
	v_fmac_f32_e32 v199, v3, v140
	v_fmac_f32_e32 v181, v4, v143
	v_fmac_f32_e32 v198, v4, v147
	v_fmac_f32_e32 v183, v3, v137
	v_fmac_f32_e32 v158, v3, v141
	v_fmac_f32_e32 v182, v4, v144
	v_fmac_f32_e32 v199, v4, v148
	v_fmac_f32_e32 v181, v5, v151
	v_fmac_f32_e32 v198, v5, v155
	v_cndmask_b32_e64 v3, v187, v180, s[4:5]
	v_fmac_f32_e32 v183, v4, v145
	v_fmac_f32_e32 v158, v4, v149
	v_fmac_f32_e32 v182, v5, v152
	v_fmac_f32_e32 v199, v5, v156
	s_waitcnt lgkmcnt(0)
	v_add_f32_e32 v2, v3, v2
	v_cndmask_b32_e64 v3, v181, v198, s[4:5]
	v_fmac_f32_e32 v183, v5, v153
	v_fmac_f32_e32 v158, v5, v157
	ds_bpermute_b32 v3, v197, v3
	v_cndmask_b32_e64 v5, v182, v199, s[4:5]
	ds_bpermute_b32 v5, v197, v5
	v_cndmask_b32_e64 v22, v183, v158, s[4:5]
	ds_bpermute_b32 v22, v197, v22
	v_cndmask_b32_e64 v4, v198, v181, s[4:5]
	s_waitcnt lgkmcnt(2)
	v_add_f32_e32 v3, v4, v3
	v_cndmask_b32_e64 v4, v199, v182, s[4:5]
	s_waitcnt lgkmcnt(1)
	v_add_f32_e32 v4, v4, v5
	v_cndmask_b32_e64 v5, v158, v183, s[4:5]
	s_waitcnt lgkmcnt(0)
	v_add_f32_e32 v5, v5, v22
	v_cndmask_b32_e64 v22, v2, v4, s[6:7]
	v_cndmask_b32_e64 v23, v3, v5, s[6:7]
	ds_bpermute_b32 v22, v196, v22
	ds_bpermute_b32 v23, v196, v23
	v_cndmask_b32_e64 v2, v4, v2, s[6:7]
	v_cndmask_b32_e64 v3, v5, v3, s[6:7]
	s_waitcnt lgkmcnt(1)
	v_add_f32_e32 v2, v2, v22
	s_waitcnt lgkmcnt(0)
	v_add_f32_e32 v3, v3, v23
	v_cndmask_b32_e64 v4, v2, v3, s[8:9]
	ds_bpermute_b32 v4, v195, v4
	v_cndmask_b32_e64 v2, v3, v2, s[8:9]
	s_waitcnt lgkmcnt(0)
	v_add_f32_e32 v2, v2, v4
	s_nop 1
	v_add_f32_dpp v2, v2, v2 row_shl:4 row_mask:0xf bank_mask:0xf
	s_nop 1
	v_add_f32_dpp v2, v2, v2 quad_perm:[2,3,0,1] row_mask:0xf bank_mask:0xf
	s_nop 1
	v_add_f32_dpp v2, v2, v2 quad_perm:[1,0,3,2] row_mask:0xf bank_mask:0xf
	s_and_saveexec_b64 s[12:13], s[10:11]
	s_cbranch_execz .LBB0_193
	v_ashrrev_i32_e32 v187, 31, v186
	v_lshlrev_b64 v[4:5], 5, v[186:187]
	s_waitcnt lgkmcnt(0)
	v_lshl_add_u64 v[4:5], v[190:191], 0, v[4:5]
	v_mul_f32_e32 v2, v193, v2
	global_store_dword v[4:5], v2, off
	s_branch .LBB0_193

; __device__ __forceinline__ unsigned pk2(float lo, float hi) { f32x2_t v = {lo, hi}; bf16x2_hw b = __builtin_convertvector(v, bf16x2_hw); return __builtin_bit_cast(unsigned, b); }
; template <bool BIN, bool WRITE_U> __device__ __forceinline__ void norm_phase(const void* hin_, const float* gain, bf16* U, const float* Wg, int ldw, int goff, int ng, float* GATE, float* RSTD, unsigned char* lds) {
;     ...
;         if (WRITE_U) { unsigned long long* o8 = (unsigned long long*)(U + (size_t)row * D_) + lane;
; #pragma unroll
;             for (int j = 0; j < 4; ++j) o8[64 * j] = (unsigned long long)pk2(v[j].x, v[j].y) | ((unsigned long long)pk2(v[j].z, v[j].w) << 32); }
;         if (ng > 0) {
;             float acc[8];
; #pragma unroll
;             for (int g = 0; g < 8; ++g) acc[g] = 0.f;
; #pragma unroll
;             for (int j = 0; j < 4; ++j)
; #pragma unroll
;                 for (int e = 0; e < 4; ++e) { const int k = 4 * (lane + 64 * j) + e; const f32x4 w0 = *(const f32x4*)(wl + k * 8), w1 = *(const f32x4*)(wl + k * 8 + 4); const float x = v[j][e];
;                     acc[0] += x * w0.x; acc[1] += x * w0.y; acc[2] += x * w0.z; acc[3] += x * w0.w; acc[4] += x * w1.x; acc[5] += x * w1.y; acc[6] += x * w1.z; acc[7] += x * w1.w; }
;             const bool h5 = (lane & 32) != 0, h4 = (lane & 16) != 0, h3 = (lane & 8) != 0;
;             float b4[4], c2[2];
; #pragma unroll
;             for (int i = 0; i < 4; ++i) { const float snd = h5 ? acc[i] : acc[i + 4], kp = h5 ? acc[i + 4] : acc[i]; b4[i] = kp + __shfl_xor(snd, 32); }
; #pragma unroll
;             for (int i = 0; i < 2; ++i) { const float snd = h4 ? b4[i] : b4[i + 2], kp = h4 ? b4[i + 2] : b4[i]; c2[i] = kp + __shfl_xor(snd, 16); }
;             float dsum; { const float snd = h3 ? c2[0] : c2[1], kp = h3 ? c2[1] : c2[0]; dsum = kp + __shfl_xor(snd, 8); }
;             dsum += __shfl_xor(dsum, 4); dsum += __shfl_xor(dsum, 2); dsum += __shfl_xor(dsum, 1);
;             if ((lane & 7) == 0) GATE[(size_t)row * 8 + ((lane >> 3) & 1) + 2 * ((lane >> 4) & 1) + 4 * ((lane >> 5) & 1)] = dsum * rstd;
.LBB0_218:
	s_or_b64 exec, exec, s[12:13]
	v_ashrrev_i32_e32 v187, 31, v186
	v_lshlrev_b64 v[180:181], 11, v[186:187]
	v_lshl_add_u64 v[180:181], v[190:191], 0, v[180:181]
	v_cvt_pk_bf16_f32 v182, v174, v175
	v_cvt_pk_bf16_f32 v183, v176, v177
	global_store_dwordx2 v[180:181], v[182:183], off
	v_cvt_pk_bf16_f32 v182, v170, v171
	v_cvt_pk_bf16_f32 v183, v172, v173
	global_store_dwordx2 v[180:181], v[182:183], off offset:512
	v_cvt_pk_bf16_f32 v182, v166, v167
	v_cvt_pk_bf16_f32 v183, v168, v169
	global_store_dwordx2 v[180:181], v[182:183], off offset:1024
	v_cvt_pk_bf16_f32 v182, v162, v163
	v_cvt_pk_bf16_f32 v183, v164, v165
	global_store_dwordx2 v[180:181], v[182:183], off offset:1536
	v_fma_f32 v180, v174, v18, 0
	v_fma_f32 v200, v174, v22, 0
	v_fmac_f32_e32 v180, v175, v26
	v_fmac_f32_e32 v200, v175, v30
	v_fmac_f32_e32 v180, v176, v34
	v_fmac_f32_e32 v200, v176, v38
	v_fmac_f32_e32 v180, v177, v42
	v_fmac_f32_e32 v200, v177, v46
	v_fma_f32 v181, v174, v19, 0
	v_fma_f32 v182, v174, v20, 0
	v_fma_f32 v183, v174, v21, 0
	v_fma_f32 v201, v174, v23, 0
	v_fma_f32 v202, v174, v24, 0
	v_fma_f32 v174, v174, v25, 0
	v_fmac_f32_e32 v180, v170, v50
	v_fmac_f32_e32 v200, v170, v54
	v_fmac_f32_e32 v181, v175, v27
	v_fmac_f32_e32 v182, v175, v28
	v_fmac_f32_e32 v183, v175, v29
	v_fmac_f32_e32 v201, v175, v31
	v_fmac_f32_e32 v202, v175, v32
	v_fmac_f32_e32 v174, v175, v33
	v_fmac_f32_e32 v180, v171, v58
	v_fmac_f32_e32 v200, v171, v62
	v_fmac_f32_e32 v181, v176, v35
	v_fmac_f32_e32 v182, v176, v36
	v_fmac_f32_e32 v183, v176, v37
	v_fmac_f32_e32 v201, v176, v39
	v_fmac_f32_e32 v202, v176, v40
	v_fmac_f32_e32 v174, v176, v41
	v_fmac_f32_e32 v180, v172, v66
	v_fmac_f32_e32 v200, v172, v70
	v_fmac_f32_e32 v181, v177, v43
	v_fmac_f32_e32 v182, v177, v44
	v_fmac_f32_e32 v183, v177, v45
	v_fmac_f32_e32 v201, v177, v47
	v_fmac_f32_e32 v202, v177, v48
	v_fmac_f32_e32 v174, v177, v49
	v_fmac_f32_e32 v180, v173, v74
	v_fmac_f32_e32 v200, v173, v78
	v_fmac_f32_e32 v181, v170, v51
	v_fmac_f32_e32 v182, v170, v52
	v_fmac_f32_e32 v183, v170, v53
	v_fmac_f32_e32 v201, v170, v55
	v_fmac_f32_e32 v202, v170, v56
	v_fmac_f32_e32 v174, v170, v57
	v_fmac_f32_e32 v180, v166, v82
	v_fmac_f32_e32 v200, v166, v86
	v_fmac_f32_e32 v181, v171, v59
	v_fmac_f32_e32 v182, v171, v60
	v_fmac_f32_e32 v183, v171, v61
	v_fmac_f32_e32 v201, v171, v63
	v_fmac_f32_e32 v202, v171, v64
	v_fmac_f32_e32 v174, v171, v65
	v_fmac_f32_e32 v180, v167, v90
	v_fmac_f32_e32 v200, v167, v94
	v_fmac_f32_e32 v181, v172, v67
	v_fmac_f32_e32 v182, v172, v68
	v_fmac_f32_e32 v183, v172, v69
	v_fmac_f32_e32 v201, v172, v71
	v_fmac_f32_e32 v202, v172, v72
	v_fmac_f32_e32 v174, v172, v73
	v_fmac_f32_e32 v180, v168, v98
	v_fmac_f32_e32 v200, v168, v102
	v_fmac_f32_e32 v181, v173, v75
	v_fmac_f32_e32 v182, v173, v76
	v_fmac_f32_e32 v183, v173, v77
	v_fmac_f32_e32 v201, v173, v79
	v_fmac_f32_e32 v202, v173, v80
	v_fmac_f32_e32 v174, v173, v81
	v_fmac_f32_e32 v180, v169, v106
	v_fmac_f32_e32 v200, v169, v110
	v_fmac_f32_e32 v181, v166, v83
	v_fmac_f32_e32 v182, v166, v84
	v_fmac_f32_e32 v183, v166, v85
	v_fmac_f32_e32 v201, v166, v87
	v_fmac_f32_e32 v202, v166, v88
	v_fmac_f32_e32 v174, v166, v89
	v_fmac_f32_e32 v180, v162, v114
	v_fmac_f32_e32 v200, v162, v118
	v_fmac_f32_e32 v181, v167, v91
	v_fmac_f32_e32 v182, v167, v92
	v_fmac_f32_e32 v183, v167, v93
	v_fmac_f32_e32 v201, v167, v95
	v_fmac_f32_e32 v202, v167, v96
	v_fmac_f32_e32 v174, v167, v97
	v_fmac_f32_e32 v180, v163, v122
	v_fmac_f32_e32 v200, v163, v126
	v_fmac_f32_e32 v181, v168, v99
	v_fmac_f32_e32 v182, v168, v100
	v_fmac_f32_e32 v183, v168, v101
	v_fmac_f32_e32 v201, v168, v103
	v_fmac_f32_e32 v202, v168, v104
	v_fmac_f32_e32 v174, v168, v105
	v_fmac_f32_e32 v180, v164, v130
	v_fmac_f32_e32 v200, v164, v134
	v_fmac_f32_e32 v181, v169, v107
	v_fmac_f32_e32 v182, v169, v108
	v_fmac_f32_e32 v183, v169, v109
	v_fmac_f32_e32 v201, v169, v111
	v_fmac_f32_e32 v202, v169, v112
	v_fmac_f32_e32 v174, v169, v113
	v_fmac_f32_e32 v180, v165, v138
	v_fmac_f32_e32 v200, v165, v142
	v_fmac_f32_e32 v181, v162, v115
	v_fmac_f32_e32 v182, v162, v116
	v_fmac_f32_e32 v183, v162, v117
	v_fmac_f32_e32 v201, v162, v119
	v_fmac_f32_e32 v202, v162, v120
	v_fmac_f32_e32 v174, v162, v121
	v_fmac_f32_e32 v181, v163, v123
	v_fmac_f32_e32 v201, v163, v127
	v_fmac_f32_e32 v181, v164, v131
	v_fmac_f32_e32 v201, v164, v135
	v_fmac_f32_e32 v182, v163, v124
	v_fmac_f32_e32 v183, v163, v125
	v_fmac_f32_e32 v202, v163, v128
	v_fmac_f32_e32 v174, v163, v129
	v_fmac_f32_e32 v181, v165, v139
	v_fmac_f32_e32 v201, v165, v143
	v_fmac_f32_e32 v182, v164, v132
	v_fmac_f32_e32 v202, v164, v136
	v_fmac_f32_e32 v183, v164, v133
	v_fmac_f32_e32 v174, v164, v137
	v_fmac_f32_e32 v182, v165, v140
	v_fmac_f32_e32 v202, v165, v144
	v_fmac_f32_e32 v183, v165, v141
	v_fmac_f32_e32 v174, v165, v145
	s_nop 1
	v_permlane32_swap_b32 v180, v200
	v_permlane32_swap_b32 v181, v201
	v_permlane32_swap_b32 v182, v202
	v_permlane32_swap_b32 v183, v174
	v_add_f32_e32 v162, v180, v200
	v_add_f32_e32 v163, v181, v201
	v_add_f32_e32 v164, v182, v202
	v_add_f32_e32 v165, v183, v174
	s_nop 1
	v_permlane16_swap_b32 v162, v164
	v_permlane16_swap_b32 v163, v165
	v_add_f32_e32 v162, v162, v164
	v_add_f32_e32 v163, v163, v165
	v_cndmask_b32_e64 v164, v162, v163, s[8:9]
	v_cndmask_b32_e64 v162, v163, v162, s[8:9]
	s_nop 0
	v_mov_b32_dpp v166, v164 row_shl:8 row_mask:0xf bank_mask:0x3
	v_mov_b32_dpp v166, v164 row_shr:8 row_mask:0xf bank_mask:0xc
	v_add_f32_e32 v162, v162, v166
	s_waitcnt lgkmcnt(0)
	s_nop 1
	v_add_f32_dpp v162, v162, v162 row_shl:4 row_mask:0xf bank_mask:0xf
	s_nop 1
	v_add_f32_dpp v162, v162, v162 quad_perm:[2,3,0,1] row_mask:0xf bank_mask:0xf
	s_nop 1
	v_add_f32_dpp v162, v162, v162 quad_perm:[1,0,3,2] row_mask:0xf bank_mask:0xf
	s_and_saveexec_b64 s[12:13], s[10:11]
	s_cbranch_execz .LBB0_213
	v_lshlrev_b64 v[164:165], 5, v[186:187]
	s_waitcnt lgkmcnt(0)
	v_lshl_add_u64 v[164:165], v[192:193], 0, v[164:165]
	v_mul_f32_e32 v162, v195, v162
	global_store_dword v[164:165], v162, off
	s_branch .LBB0_213
